# G1 GEMM epilogue: the four serialized load-8-partials + vmcnt(0) round trips hoisted to the top of the epilogue, pipelined through four row buffers, factors kept in v172-v179
# baseline (speedup 1.0000x reference)
;     __device__ __forceinline__ void apply(const Ld& d, int row, int c0, int, int, int, const f32x4& a0, const f32x4& b0, const f32x4& a1, const f32x4& b1) const { half(d.g0, row, c0, a0, b0); half(d.g1, row, c0 + 128, a1, b1); }
;     __device__ __forceinline__ void apply(const Ld& d, int row, int c0, int, int, int, const f32x4& a0, const f32x4& b0, const f32x4& a1, const f32x4& b1) const { half(d.g0, d.p0, row, c0, a0, b0); half(d.g1, d.p1, row, c0 + 128, a1, b1); }
;     __device__ __forceinline__ void operator()(const f32x4 (&acc)[2][2][4][2], const Unit& u, int wr, int wc, int fr, int fq) const {
;         const int c0 = u.pn * BM + wc * 32 + 8 * fq;
; #pragma unroll
;         for (int ai = 0; ai < 2; ++ai)
; #pragma unroll
;             for (int mp = 0; mp < 4; mp += 2) {
;                 typename F::Ld ld[2];
; #pragma unroll
;                 for (int m = 0; m < 2; ++m) f.load(ld[m], u.pm * BM + ai * HALF + wr * 64 + (mp + m) * 16 + fr, c0, u.pn, fq);
;     __device__ __forceinline__ void load(Ld& d, int row, int, int, int) const {
; #pragma unroll
;         for (int i = 0; i < 4; ++i) d.p[i] = ((const f32x4*)(ssqh + (size_t)row * 16))[i]; }
;     __device__ __forceinline__ void apply(const Ld& d, int row, int c0, int pn, int wc, int fq, const f32x4& a0, const f32x4& b0, const f32x4& a1, const f32x4& b1) const {
;         const f32x4 t = (d.p[0] + d.p[1]) + (d.p[2] + d.p[3]);
;         const float inv = __builtin_amdgcn_rsqf(((t[0] + t[1]) + (t[2] + t[3])) * (1.f / DM) + EPS);
.LBB0_295:
	s_andn2_b64 vcc, exec, s[0:1]
	s_cbranch_vccnz .LBB0_432
	s_lshl_b32 s63, s63, 8
	v_add_u32_e32 v152, s63, v17
	v_ashrrev_i32_e32 v153, 31, v152
	v_lshlrev_b64 v[158:159], 6, v[152:153]
	v_lshl_add_u64 v[180:181], s[24:25], 0, v[158:159]
	s_movk_i32 s36, 0x2000
	s_mov_b32 s37, 0
	global_load_dwordx4 v[134:137], v[180:181], off
	global_load_dwordx4 v[138:141], v[180:181], off offset:16
	global_load_dwordx4 v[142:145], v[180:181], off offset:32
	global_load_dwordx4 v[146:149], v[180:181], off offset:48
	global_load_dwordx4 v[154:157], v[180:181], off offset:1024
	global_load_dwordx4 v[160:163], v[180:181], off offset:1040
	global_load_dwordx4 v[164:167], v[180:181], off offset:1056
	global_load_dwordx4 v[168:171], v[180:181], off offset:1072
	v_lshl_add_u64 v[230:231], v[180:181], 0, s[36:37]
	global_load_dwordx4 v[204:207], v[180:181], off offset:2048
	global_load_dwordx4 v[208:211], v[180:181], off offset:2064
	global_load_dwordx4 v[212:215], v[180:181], off offset:2080
	global_load_dwordx4 v[216:219], v[180:181], off offset:2096
	global_load_dwordx4 v[220:223], v[180:181], off offset:3072
	global_load_dwordx4 v[224:227], v[180:181], off offset:3088
	global_load_dwordx4 v[244:247], v[180:181], off offset:3104
	global_load_dwordx4 v[248:251], v[180:181], off offset:3120
	s_waitcnt vmcnt(12)
	v_pk_add_f32 v[136:137], v[136:137], v[140:141]
	v_pk_add_f32 v[134:135], v[134:135], v[138:139]
	v_pk_add_f32 v[138:139], v[144:145], v[148:149]
	v_pk_add_f32 v[140:141], v[142:143], v[146:147]
	v_pk_add_f32 v[136:137], v[136:137], v[138:139]
	v_pk_add_f32 v[134:135], v[134:135], v[140:141]
	s_nop 0
	v_pk_mov_b32 v[142:143], v[134:135], v[136:137] op_sel:[1,0]
	v_mov_b32_e32 v135, v137
	v_pk_add_f32 v[134:135], v[142:143], v[134:135]
	s_nop 0
	v_add_f32_e32 v172, v134, v135
	v_fmamk_f32 v172, v172, 0x3a800000, v229
	v_rsq_f32_e32 v172, v172
	global_load_dwordx4 v[134:137], v[230:231], off
	global_load_dwordx4 v[138:141], v[230:231], off offset:16
	global_load_dwordx4 v[142:145], v[230:231], off offset:32
	global_load_dwordx4 v[146:149], v[230:231], off offset:48
	s_waitcnt vmcnt(12)
	v_pk_add_f32 v[156:157], v[156:157], v[162:163]
	v_pk_add_f32 v[154:155], v[154:155], v[160:161]
	v_pk_add_f32 v[160:161], v[166:167], v[170:171]
	v_pk_add_f32 v[162:163], v[164:165], v[168:169]
	v_pk_add_f32 v[156:157], v[156:157], v[160:161]
	v_pk_add_f32 v[154:155], v[154:155], v[162:163]
	s_nop 0
	v_pk_mov_b32 v[164:165], v[154:155], v[156:157] op_sel:[1,0]
	v_mov_b32_e32 v155, v157
	v_pk_add_f32 v[154:155], v[164:165], v[154:155]
	s_nop 0
	v_add_f32_e32 v173, v154, v155
	v_fmamk_f32 v173, v173, 0x3a800000, v229
	v_rsq_f32_e32 v173, v173
	global_load_dwordx4 v[154:157], v[230:231], off offset:1024
	global_load_dwordx4 v[160:163], v[230:231], off offset:1040
	global_load_dwordx4 v[164:167], v[230:231], off offset:1056
	global_load_dwordx4 v[168:171], v[230:231], off offset:1072
	s_waitcnt vmcnt(12)
	v_pk_add_f32 v[206:207], v[206:207], v[210:211]
	v_pk_add_f32 v[204:205], v[204:205], v[208:209]
	v_pk_add_f32 v[208:209], v[214:215], v[218:219]
	v_pk_add_f32 v[210:211], v[212:213], v[216:217]
	v_pk_add_f32 v[206:207], v[206:207], v[208:209]
	v_pk_add_f32 v[204:205], v[204:205], v[210:211]
	s_nop 0
	v_pk_mov_b32 v[212:213], v[204:205], v[206:207] op_sel:[1,0]
	v_mov_b32_e32 v205, v207
	v_pk_add_f32 v[204:205], v[212:213], v[204:205]
	s_nop 0
	v_add_f32_e32 v174, v204, v205
	v_fmamk_f32 v174, v174, 0x3a800000, v229
	v_rsq_f32_e32 v174, v174
	global_load_dwordx4 v[204:207], v[230:231], off offset:2048
	global_load_dwordx4 v[208:211], v[230:231], off offset:2064
	global_load_dwordx4 v[212:215], v[230:231], off offset:2080
	global_load_dwordx4 v[216:219], v[230:231], off offset:2096
	s_waitcnt vmcnt(12)
; __device__ __forceinline__ u32x4 pack8(const f32x4& a, const f32x4& b) { u32x4 w; w.x = cvt_pk_bf16(a[0], a[1]); w.y = cvt_pk_bf16(a[2], a[3]); w.z = cvt_pk_bf16(b[0], b[1]); w.w = cvt_pk_bf16(b[2], b[3]); return w; }
;     __device__ __forceinline__ void apply(const Ld& d, int row, int c0, int, int, int, const f32x4& a0, const f32x4& b0, const f32x4& a1, const f32x4& b1) const { half(d.g0, row, c0, a0, b0); half(d.g1, row, c0 + 128, a1, b1); }
;     __device__ __forceinline__ void apply(const Ld& d, int row, int c0, int, int, int, const f32x4& a0, const f32x4& b0, const f32x4& a1, const f32x4& b1) const { half(d.g0, d.p0, row, c0, a0, b0); half(d.g1, d.p1, row, c0 + 128, a1, b1); }
;     __device__ __forceinline__ void load(Ld& d, int row, int, int, int) const {
; #pragma unroll
;         for (int i = 0; i < 4; ++i) d.p[i] = ((const f32x4*)(ssqh + (size_t)row * 16))[i]; }
;     __device__ __forceinline__ void apply(const Ld& d, int row, int c0, int pn, int wc, int fq, const f32x4& a0, const f32x4& b0, const f32x4& a1, const f32x4& b1) const {
;         const f32x4 t = (d.p[0] + d.p[1]) + (d.p[2] + d.p[3]);
;         const float inv = __builtin_amdgcn_rsqf(((t[0] + t[1]) + (t[2] + t[3])) * (1.f / DM) + EPS);
;         const f32x4 v0 = a0 * inv, v1 = b0 * inv, v2 = a1 * inv, v3 = b1 * inv;
;         if (pn < 18) { *(u32x4*)(proj + (size_t)row * PW + c0) = pack8(v0, v1); *(u32x4*)(proj + (size_t)row * PW + c0 + 128) = pack8(v2, v3); }
	v_pk_add_f32 v[222:223], v[222:223], v[226:227]
	v_pk_add_f32 v[220:221], v[220:221], v[224:225]
	v_pk_add_f32 v[224:225], v[246:247], v[250:251]
	v_pk_add_f32 v[226:227], v[244:245], v[248:249]
	v_pk_add_f32 v[222:223], v[222:223], v[224:225]
	v_pk_add_f32 v[220:221], v[220:221], v[226:227]
	s_nop 0
	v_pk_mov_b32 v[244:245], v[220:221], v[222:223] op_sel:[1,0]
	v_mov_b32_e32 v221, v223
	v_pk_add_f32 v[220:221], v[244:245], v[220:221]
	s_nop 0
	v_add_f32_e32 v175, v220, v221
	v_fmamk_f32 v175, v175, 0x3a800000, v229
	v_rsq_f32_e32 v175, v175
	global_load_dwordx4 v[220:223], v[230:231], off offset:3072
	global_load_dwordx4 v[224:227], v[230:231], off offset:3088
	global_load_dwordx4 v[244:247], v[230:231], off offset:3104
	global_load_dwordx4 v[248:251], v[230:231], off offset:3120
	s_waitcnt vmcnt(12)
	v_pk_add_f32 v[136:137], v[136:137], v[140:141]
	v_pk_add_f32 v[134:135], v[134:135], v[138:139]
	v_pk_add_f32 v[138:139], v[144:145], v[148:149]
	v_pk_add_f32 v[140:141], v[142:143], v[146:147]
	v_pk_add_f32 v[136:137], v[136:137], v[138:139]
	v_pk_add_f32 v[134:135], v[134:135], v[140:141]
	s_nop 0
	v_pk_mov_b32 v[142:143], v[134:135], v[136:137] op_sel:[1,0]
	v_mov_b32_e32 v135, v137
	v_pk_add_f32 v[134:135], v[142:143], v[134:135]
	s_nop 0
	v_add_f32_e32 v176, v134, v135
	v_fmamk_f32 v176, v176, 0x3a800000, v229
	v_rsq_f32_e32 v176, v176
	s_waitcnt vmcnt(8)
	v_pk_add_f32 v[156:157], v[156:157], v[162:163]
	v_pk_add_f32 v[154:155], v[154:155], v[160:161]
	v_pk_add_f32 v[160:161], v[166:167], v[170:171]
	v_pk_add_f32 v[162:163], v[164:165], v[168:169]
	v_pk_add_f32 v[156:157], v[156:157], v[160:161]
	v_pk_add_f32 v[154:155], v[154:155], v[162:163]
	s_nop 0
	v_pk_mov_b32 v[164:165], v[154:155], v[156:157] op_sel:[1,0]
	v_mov_b32_e32 v155, v157
	v_pk_add_f32 v[154:155], v[164:165], v[154:155]
	s_nop 0
	v_add_f32_e32 v177, v154, v155
	v_fmamk_f32 v177, v177, 0x3a800000, v229
	v_rsq_f32_e32 v177, v177
	s_waitcnt vmcnt(4)
	v_pk_add_f32 v[206:207], v[206:207], v[210:211]
	v_pk_add_f32 v[204:205], v[204:205], v[208:209]
	v_pk_add_f32 v[208:209], v[214:215], v[218:219]
	v_pk_add_f32 v[210:211], v[212:213], v[216:217]
	v_pk_add_f32 v[206:207], v[206:207], v[208:209]
	v_pk_add_f32 v[204:205], v[204:205], v[210:211]
	s_nop 0
	v_pk_mov_b32 v[212:213], v[204:205], v[206:207] op_sel:[1,0]
	v_mov_b32_e32 v205, v207
	v_pk_add_f32 v[204:205], v[212:213], v[204:205]
	s_nop 0
	v_add_f32_e32 v178, v204, v205
	v_fmamk_f32 v178, v178, 0x3a800000, v229
	v_rsq_f32_e32 v178, v178
	s_waitcnt vmcnt(0)
	v_pk_add_f32 v[222:223], v[222:223], v[226:227]
	v_pk_add_f32 v[220:221], v[220:221], v[224:225]
	v_pk_add_f32 v[224:225], v[246:247], v[250:251]
	v_pk_add_f32 v[226:227], v[244:245], v[248:249]
	v_pk_add_f32 v[222:223], v[222:223], v[224:225]
	v_pk_add_f32 v[220:221], v[220:221], v[226:227]
	s_nop 0
	v_pk_mov_b32 v[244:245], v[220:221], v[222:223] op_sel:[1,0]
	v_mov_b32_e32 v221, v223
	v_pk_add_f32 v[220:221], v[244:245], v[220:221]
	s_nop 0
	v_add_f32_e32 v179, v220, v221
	v_fmamk_f32 v179, v179, 0x3a800000, v229
	v_rsq_f32_e32 v179, v179
	v_or_b32_e32 v134, 16, v152
	v_ashrrev_i32_e32 v135, 31, v134
	v_lshlrev_b64 v[134:135], 6, v[134:135]
	v_lshl_add_u64 v[146:147], s[24:25], 0, v[134:135]
	v_lshl_or_b32 v150, s71, 8, v241
	s_movk_i32 s0, 0x1220
	s_cmp_gt_i32 s71, 17
	v_cmp_gt_i32_e64 s[40:41], s0, v150
	s_cselect_b64 s[0:1], -1, 0
	s_and_b64 vcc, exec, s[0:1]
	v_mov_b32_e32 v0, v172
	s_nop 0
	v_pk_mul_f32 v[132:133], v[132:133], v[0:1] op_sel_hi:[1,0]
	v_pk_mul_f32 v[130:131], v[130:131], v[0:1] op_sel_hi:[1,0]
	v_pk_mul_f32 v[154:155], v[128:129], v[0:1] op_sel_hi:[1,0]
	v_pk_mul_f32 v[156:157], v[126:127], v[0:1] op_sel_hi:[1,0]
	s_cbranch_vccz .LBB0_309
	s_mov_b64 s[42:43], 0
	s_mov_b64 s[22:23], 0
	s_and_saveexec_b64 s[44:45], s[40:41]
	s_xor_b64 s[44:45], exec, s[44:45]
	s_cbranch_execz .LBB0_299
	v_readlane_b32 s36, v255, 22
	v_readlane_b32 s37, v255, 23
	s_mov_b64 s[22:23], exec
	v_cvt_pk_bf16_f32 v126, v130, v131
	v_cvt_pk_bf16_f32 v127, v132, v133
	v_cvt_pk_bf16_f32 v128, v156, v157
	v_cvt_pk_bf16_f32 v129, v154, v155
	s_nop 0
	v_lshl_add_u64 v[160:161], s[36:37], 0, v[158:159]

; __device__ __forceinline__ u32x4 pack8(const f32x4& a, const f32x4& b) { u32x4 w; w.x = cvt_pk_bf16(a[0], a[1]); w.y = cvt_pk_bf16(a[2], a[3]); w.z = cvt_pk_bf16(b[0], b[1]); w.w = cvt_pk_bf16(b[2], b[3]); return w; }
;     __device__ __forceinline__ void apply(const Ld& d, int row, int c0, int, int, int, const f32x4& a0, const f32x4& b0, const f32x4& a1, const f32x4& b1) const { half(d.g0, row, c0, a0, b0); half(d.g1, row, c0 + 128, a1, b1); }
;     __device__ __forceinline__ void apply(const Ld& d, int row, int c0, int, int, int, const f32x4& a0, const f32x4& b0, const f32x4& a1, const f32x4& b1) const { half(d.g0, d.p0, row, c0, a0, b0); half(d.g1, d.p1, row, c0 + 128, a1, b1); }
;     __device__ __forceinline__ void apply(const Ld& d, int row, int c0, int pn, int wc, int fq, const f32x4& a0, const f32x4& b0, const f32x4& a1, const f32x4& b1) const {
;         const f32x4 t = (d.p[0] + d.p[1]) + (d.p[2] + d.p[3]);
;         const float inv = __builtin_amdgcn_rsqf(((t[0] + t[1]) + (t[2] + t[3])) * (1.f / DM) + EPS);
;         const f32x4 v0 = a0 * inv, v1 = b0 * inv, v2 = a1 * inv, v3 = b1 * inv;
;         if (pn < 18) { *(u32x4*)(proj + (size_t)row * PW + c0) = pack8(v0, v1); *(u32x4*)(proj + (size_t)row * PW + c0 + 128) = pack8(v2, v3); }
.LBB0_322:
	s_andn2_b64 vcc, exec, s[0:1]
	v_mov_b32_e32 v0, v173
	v_add_u32_e32 v118, s63, v235
	v_pk_mul_f32 v[120:121], v[112:113], v[0:1] op_sel_hi:[1,0]
	v_cndmask_b32_e64 v112, 0, 1, s[0:1]
	v_pk_mul_f32 v[116:117], v[116:117], v[0:1] op_sel_hi:[1,0]
	v_pk_mul_f32 v[114:115], v[114:115], v[0:1] op_sel_hi:[1,0]
	v_cmp_ne_u32_e64 s[42:43], 1, v112
	v_pk_mul_f32 v[122:123], v[110:111], v[0:1] op_sel_hi:[1,0]
	s_cbranch_vccnz .LBB0_326
	s_mov_b64 s[44:45], 0
	s_mov_b64 s[0:1], 0
	s_and_saveexec_b64 vcc, s[40:41]
	s_cbranch_execz .LBB0_325
	v_ashrrev_i32_e32 v119, 31, v118
	v_readlane_b32 s36, v255, 22
	v_lshlrev_b64 v[124:125], 6, v[118:119]
	v_readlane_b32 s37, v255, 23
	s_mov_b64 s[0:1], exec
	v_cvt_pk_bf16_f32 v110, v114, v115
	v_cvt_pk_bf16_f32 v111, v116, v117
	v_cvt_pk_bf16_f32 v112, v122, v123
	v_cvt_pk_bf16_f32 v113, v120, v121
	s_nop 0
	v_lshl_add_u64 v[124:125], s[36:37], 0, v[124:125]

; __device__ __forceinline__ u32x4 pack8(const f32x4& a, const f32x4& b) { u32x4 w; w.x = cvt_pk_bf16(a[0], a[1]); w.y = cvt_pk_bf16(a[2], a[3]); w.z = cvt_pk_bf16(b[0], b[1]); w.w = cvt_pk_bf16(b[2], b[3]); return w; }
;     __device__ __forceinline__ void apply(const Ld& d, int row, int c0, int, int, int, const f32x4& a0, const f32x4& b0, const f32x4& a1, const f32x4& b1) const { half(d.g0, row, c0, a0, b0); half(d.g1, row, c0 + 128, a1, b1); }
;     __device__ __forceinline__ void apply(const Ld& d, int row, int c0, int, int, int, const f32x4& a0, const f32x4& b0, const f32x4& a1, const f32x4& b1) const { half(d.g0, d.p0, row, c0, a0, b0); half(d.g1, d.p1, row, c0 + 128, a1, b1); }
;     __device__ __forceinline__ void apply(const Ld& d, int row, int c0, int pn, int wc, int fq, const f32x4& a0, const f32x4& b0, const f32x4& a1, const f32x4& b1) const {
;         const f32x4 t = (d.p[0] + d.p[1]) + (d.p[2] + d.p[3]);
;         const float inv = __builtin_amdgcn_rsqf(((t[0] + t[1]) + (t[2] + t[3])) * (1.f / DM) + EPS);
;         const f32x4 v0 = a0 * inv, v1 = b0 * inv, v2 = a1 * inv, v3 = b1 * inv;
;         if (pn < 18) { *(u32x4*)(proj + (size_t)row * PW + c0) = pack8(v0, v1); *(u32x4*)(proj + (size_t)row * PW + c0 + 128) = pack8(v2, v3); }
.LBB0_339:
	v_or_b32_e32 v102, 32, v152
	v_ashrrev_i32_e32 v103, 31, v102
	v_lshlrev_b64 v[102:103], 6, v[102:103]
	v_lshl_add_u64 v[102:103], s[24:25], 0, v[102:103]
	v_or_b32_e32 v102, 48, v152
	v_ashrrev_i32_e32 v103, 31, v102
	v_lshlrev_b64 v[102:103], 6, v[102:103]
	v_lshl_add_u64 v[114:115], s[24:25], 0, v[102:103]
	s_and_b64 vcc, exec, s[42:43]
	v_mov_b32_e32 v0, v174
	v_add_u32_e32 v118, s63, v236
	v_pk_mul_f32 v[100:101], v[100:101], v[0:1] op_sel_hi:[1,0]
	v_pk_mul_f32 v[98:99], v[98:99], v[0:1] op_sel_hi:[1,0]
	v_pk_mul_f32 v[120:121], v[96:97], v[0:1] op_sel_hi:[1,0]
	v_pk_mul_f32 v[122:123], v[94:95], v[0:1] op_sel_hi:[1,0]
	s_cbranch_vccnz .LBB0_343
	s_mov_b64 s[22:23], 0
	s_mov_b64 s[0:1], 0
	s_and_saveexec_b64 vcc, s[40:41]
	s_cbranch_execz .LBB0_342
	v_ashrrev_i32_e32 v119, 31, v118
	v_readlane_b32 s36, v255, 22
	v_lshlrev_b64 v[124:125], 6, v[118:119]
	v_readlane_b32 s37, v255, 23
	s_mov_b64 s[0:1], exec
	v_cvt_pk_bf16_f32 v94, v98, v99
	v_cvt_pk_bf16_f32 v95, v100, v101
	v_cvt_pk_bf16_f32 v96, v122, v123
	v_cvt_pk_bf16_f32 v97, v120, v121
	s_nop 0
	v_lshl_add_u64 v[124:125], s[36:37], 0, v[124:125]

; __device__ __forceinline__ u32x4 pack8(const f32x4& a, const f32x4& b) { u32x4 w; w.x = cvt_pk_bf16(a[0], a[1]); w.y = cvt_pk_bf16(a[2], a[3]); w.z = cvt_pk_bf16(b[0], b[1]); w.w = cvt_pk_bf16(b[2], b[3]); return w; }
;     __device__ __forceinline__ void apply(const Ld& d, int row, int c0, int, int, int, const f32x4& a0, const f32x4& b0, const f32x4& a1, const f32x4& b1) const { half(d.g0, row, c0, a0, b0); half(d.g1, row, c0 + 128, a1, b1); }
;     __device__ __forceinline__ void apply(const Ld& d, int row, int c0, int, int, int, const f32x4& a0, const f32x4& b0, const f32x4& a1, const f32x4& b1) const { half(d.g0, d.p0, row, c0, a0, b0); half(d.g1, d.p1, row, c0 + 128, a1, b1); }
;     __device__ __forceinline__ void apply(const Ld& d, int row, int c0, int pn, int wc, int fq, const f32x4& a0, const f32x4& b0, const f32x4& a1, const f32x4& b1) const {
;         const f32x4 t = (d.p[0] + d.p[1]) + (d.p[2] + d.p[3]);
;         const float inv = __builtin_amdgcn_rsqf(((t[0] + t[1]) + (t[2] + t[3])) * (1.f / DM) + EPS);
;         const f32x4 v0 = a0 * inv, v1 = b0 * inv, v2 = a1 * inv, v3 = b1 * inv;
;         if (pn < 18) { *(u32x4*)(proj + (size_t)row * PW + c0) = pack8(v0, v1); *(u32x4*)(proj + (size_t)row * PW + c0 + 128) = pack8(v2, v3); }
.LBB0_356:
	s_and_b64 vcc, exec, s[42:43]
	v_mov_b32_e32 v0, v175
	v_add_u32_e32 v86, s63, v237
	v_pk_mul_f32 v[84:85], v[84:85], v[0:1] op_sel_hi:[1,0]
	v_pk_mul_f32 v[82:83], v[82:83], v[0:1] op_sel_hi:[1,0]
	v_pk_mul_f32 v[88:89], v[80:81], v[0:1] op_sel_hi:[1,0]
	v_pk_mul_f32 v[90:91], v[78:79], v[0:1] op_sel_hi:[1,0]
	s_cbranch_vccnz .LBB0_360
	s_mov_b64 s[22:23], 0
	s_mov_b64 s[0:1], 0
	s_and_saveexec_b64 vcc, s[40:41]
	s_cbranch_execz .LBB0_359
	v_ashrrev_i32_e32 v87, 31, v86
	v_readlane_b32 s36, v255, 22
	v_lshlrev_b64 v[92:93], 6, v[86:87]
	v_readlane_b32 s37, v255, 23
	s_mov_b64 s[0:1], exec
	v_cvt_pk_bf16_f32 v78, v82, v83
	v_cvt_pk_bf16_f32 v79, v84, v85
	v_cvt_pk_bf16_f32 v80, v90, v91
	v_cvt_pk_bf16_f32 v81, v88, v89
	s_nop 0
	v_lshl_add_u64 v[92:93], s[36:37], 0, v[92:93]

; __device__ __forceinline__ u32x4 pack8(const f32x4& a, const f32x4& b) { u32x4 w; w.x = cvt_pk_bf16(a[0], a[1]); w.y = cvt_pk_bf16(a[2], a[3]); w.z = cvt_pk_bf16(b[0], b[1]); w.w = cvt_pk_bf16(b[2], b[3]); return w; }
;     __device__ __forceinline__ void apply(const Ld& d, int row, int c0, int, int, int, const f32x4& a0, const f32x4& b0, const f32x4& a1, const f32x4& b1) const { half(d.g0, row, c0, a0, b0); half(d.g1, row, c0 + 128, a1, b1); }
;     __device__ __forceinline__ void apply(const Ld& d, int row, int c0, int, int, int, const f32x4& a0, const f32x4& b0, const f32x4& a1, const f32x4& b1) const { half(d.g0, d.p0, row, c0, a0, b0); half(d.g1, d.p1, row, c0 + 128, a1, b1); }
;     __device__ __forceinline__ void apply(const Ld& d, int row, int c0, int pn, int wc, int fq, const f32x4& a0, const f32x4& b0, const f32x4& a1, const f32x4& b1) const {
;         const f32x4 t = (d.p[0] + d.p[1]) + (d.p[2] + d.p[3]);
;         const float inv = __builtin_amdgcn_rsqf(((t[0] + t[1]) + (t[2] + t[3])) * (1.f / DM) + EPS);
;         const f32x4 v0 = a0 * inv, v1 = b0 * inv, v2 = a1 * inv, v3 = b1 * inv;
;         if (pn < 18) { *(u32x4*)(proj + (size_t)row * PW + c0) = pack8(v0, v1); *(u32x4*)(proj + (size_t)row * PW + c0 + 128) = pack8(v2, v3); }
.LBB0_373:
	v_add_u32_e32 v86, 0x80, v152
	v_ashrrev_i32_e32 v87, 31, v86
	v_lshlrev_b64 v[96:97], 6, v[86:87]
	v_lshl_add_u64 v[70:71], s[24:25], 0, v[96:97]
	v_add_u32_e32 v88, 0x90, v152
	v_ashrrev_i32_e32 v89, 31, v88
	v_lshlrev_b64 v[70:71], 6, v[88:89]
	v_lshl_add_u64 v[82:83], s[24:25], 0, v[70:71]
	s_and_b64 vcc, exec, s[42:43]
	v_mov_b32_e32 v0, v176
	s_nop 0
	v_pk_mul_f32 v[68:69], v[68:69], v[0:1] op_sel_hi:[1,0]
	v_pk_mul_f32 v[66:67], v[66:67], v[0:1] op_sel_hi:[1,0]
	v_pk_mul_f32 v[90:91], v[64:65], v[0:1] op_sel_hi:[1,0]
	v_pk_mul_f32 v[92:93], v[62:63], v[0:1] op_sel_hi:[1,0]
	s_cbranch_vccnz .LBB0_377
	s_mov_b64 s[22:23], 0
	s_mov_b64 s[0:1], 0
	s_and_saveexec_b64 vcc, s[40:41]
	s_cbranch_execz .LBB0_376
	v_readlane_b32 s36, v255, 22
	v_readlane_b32 s37, v255, 23
	s_mov_b64 s[0:1], exec
	v_cvt_pk_bf16_f32 v62, v66, v67
	v_cvt_pk_bf16_f32 v63, v68, v69
	v_cvt_pk_bf16_f32 v64, v92, v93
	v_cvt_pk_bf16_f32 v65, v90, v91
	s_nop 0
	v_lshl_add_u64 v[94:95], s[36:37], 0, v[96:97]

; __device__ __forceinline__ u32x4 pack8(const f32x4& a, const f32x4& b) { u32x4 w; w.x = cvt_pk_bf16(a[0], a[1]); w.y = cvt_pk_bf16(a[2], a[3]); w.z = cvt_pk_bf16(b[0], b[1]); w.w = cvt_pk_bf16(b[2], b[3]); return w; }
;     __device__ __forceinline__ void apply(const Ld& d, int row, int c0, int, int, int, const f32x4& a0, const f32x4& b0, const f32x4& a1, const f32x4& b1) const { half(d.g0, row, c0, a0, b0); half(d.g1, row, c0 + 128, a1, b1); }
;     __device__ __forceinline__ void apply(const Ld& d, int row, int c0, int, int, int, const f32x4& a0, const f32x4& b0, const f32x4& a1, const f32x4& b1) const { half(d.g0, d.p0, row, c0, a0, b0); half(d.g1, d.p1, row, c0 + 128, a1, b1); }
;     __device__ __forceinline__ void apply(const Ld& d, int row, int c0, int pn, int wc, int fq, const f32x4& a0, const f32x4& b0, const f32x4& a1, const f32x4& b1) const {
;         const f32x4 t = (d.p[0] + d.p[1]) + (d.p[2] + d.p[3]);
;         const float inv = __builtin_amdgcn_rsqf(((t[0] + t[1]) + (t[2] + t[3])) * (1.f / DM) + EPS);
;         const f32x4 v0 = a0 * inv, v1 = b0 * inv, v2 = a1 * inv, v3 = b1 * inv;
;         if (pn < 18) { *(u32x4*)(proj + (size_t)row * PW + c0) = pack8(v0, v1); *(u32x4*)(proj + (size_t)row * PW + c0 + 128) = pack8(v2, v3); }
.LBB0_390:
	s_and_b64 vcc, exec, s[42:43]
	v_mov_b32_e32 v0, v177
	s_nop 0
	v_pk_mul_f32 v[52:53], v[52:53], v[0:1] op_sel_hi:[1,0]
	v_pk_mul_f32 v[50:51], v[50:51], v[0:1] op_sel_hi:[1,0]
	v_pk_mul_f32 v[54:55], v[48:49], v[0:1] op_sel_hi:[1,0]
	v_pk_mul_f32 v[56:57], v[46:47], v[0:1] op_sel_hi:[1,0]
	s_cbranch_vccnz .LBB0_394
	s_mov_b64 s[22:23], 0
	s_mov_b64 s[0:1], 0
	s_and_saveexec_b64 vcc, s[40:41]
	s_cbranch_execz .LBB0_393
	v_readlane_b32 s36, v255, 22
	v_lshlrev_b64 v[58:59], 6, v[88:89]
	v_readlane_b32 s37, v255, 23
	s_mov_b64 s[0:1], exec
	v_cvt_pk_bf16_f32 v46, v50, v51
	v_cvt_pk_bf16_f32 v47, v52, v53
	v_cvt_pk_bf16_f32 v48, v56, v57
	v_cvt_pk_bf16_f32 v49, v54, v55
	s_nop 0
	v_lshl_add_u64 v[58:59], s[36:37], 0, v[58:59]

; __device__ __forceinline__ u32x4 pack8(const f32x4& a, const f32x4& b) { u32x4 w; w.x = cvt_pk_bf16(a[0], a[1]); w.y = cvt_pk_bf16(a[2], a[3]); w.z = cvt_pk_bf16(b[0], b[1]); w.w = cvt_pk_bf16(b[2], b[3]); return w; }
;     __device__ __forceinline__ void apply(const Ld& d, int row, int c0, int, int, int, const f32x4& a0, const f32x4& b0, const f32x4& a1, const f32x4& b1) const { half(d.g0, row, c0, a0, b0); half(d.g1, row, c0 + 128, a1, b1); }
;     __device__ __forceinline__ void apply(const Ld& d, int row, int c0, int, int, int, const f32x4& a0, const f32x4& b0, const f32x4& a1, const f32x4& b1) const { half(d.g0, d.p0, row, c0, a0, b0); half(d.g1, d.p1, row, c0 + 128, a1, b1); }
;     __device__ __forceinline__ void apply(const Ld& d, int row, int c0, int pn, int wc, int fq, const f32x4& a0, const f32x4& b0, const f32x4& a1, const f32x4& b1) const {
;         const f32x4 t = (d.p[0] + d.p[1]) + (d.p[2] + d.p[3]);
;         const float inv = __builtin_amdgcn_rsqf(((t[0] + t[1]) + (t[2] + t[3])) * (1.f / DM) + EPS);
;         const f32x4 v0 = a0 * inv, v1 = b0 * inv, v2 = a1 * inv, v3 = b1 * inv;
;         if (pn < 18) { *(u32x4*)(proj + (size_t)row * PW + c0) = pack8(v0, v1); *(u32x4*)(proj + (size_t)row * PW + c0 + 128) = pack8(v2, v3); }
.LBB0_407:
	v_or_b32_e32 v38, 32, v86
	v_ashrrev_i32_e32 v39, 31, v38
	v_lshlrev_b64 v[38:39], 6, v[38:39]
	v_lshl_add_u64 v[38:39], s[24:25], 0, v[38:39]
	v_or_b32_e32 v38, 48, v86
	v_ashrrev_i32_e32 v39, 31, v38
	v_lshlrev_b64 v[38:39], 6, v[38:39]
	v_lshl_add_u64 v[50:51], s[24:25], 0, v[38:39]
	s_and_b64 vcc, exec, s[42:43]
	v_mov_b32_e32 v0, v178
	v_add_u32_e32 v54, 0xa0, v152
	v_pk_mul_f32 v[36:37], v[36:37], v[0:1] op_sel_hi:[1,0]
	v_pk_mul_f32 v[34:35], v[34:35], v[0:1] op_sel_hi:[1,0]
	v_pk_mul_f32 v[56:57], v[32:33], v[0:1] op_sel_hi:[1,0]
	v_pk_mul_f32 v[58:59], v[30:31], v[0:1] op_sel_hi:[1,0]
	s_cbranch_vccnz .LBB0_411
	s_mov_b64 s[22:23], 0
	s_mov_b64 s[0:1], 0
	s_and_saveexec_b64 vcc, s[40:41]
	s_cbranch_execz .LBB0_410
	v_ashrrev_i32_e32 v55, 31, v54
	v_readlane_b32 s36, v255, 22
	v_lshlrev_b64 v[60:61], 6, v[54:55]
	v_readlane_b32 s37, v255, 23
	s_mov_b64 s[0:1], exec
	v_cvt_pk_bf16_f32 v30, v34, v35
	v_cvt_pk_bf16_f32 v31, v36, v37
	v_cvt_pk_bf16_f32 v32, v58, v59
	v_cvt_pk_bf16_f32 v33, v56, v57
	s_nop 0
	v_lshl_add_u64 v[60:61], s[36:37], 0, v[60:61]

; __device__ __forceinline__ u32x4 pack8(const f32x4& a, const f32x4& b) { u32x4 w; w.x = cvt_pk_bf16(a[0], a[1]); w.y = cvt_pk_bf16(a[2], a[3]); w.z = cvt_pk_bf16(b[0], b[1]); w.w = cvt_pk_bf16(b[2], b[3]); return w; }
;     __device__ __forceinline__ void apply(const Ld& d, int row, int c0, int, int, int, const f32x4& a0, const f32x4& b0, const f32x4& a1, const f32x4& b1) const { half(d.g0, row, c0, a0, b0); half(d.g1, row, c0 + 128, a1, b1); }
;     __device__ __forceinline__ void apply(const Ld& d, int row, int c0, int, int, int, const f32x4& a0, const f32x4& b0, const f32x4& a1, const f32x4& b1) const { half(d.g0, d.p0, row, c0, a0, b0); half(d.g1, d.p1, row, c0 + 128, a1, b1); }
;     __device__ __forceinline__ void apply(const Ld& d, int row, int c0, int pn, int wc, int fq, const f32x4& a0, const f32x4& b0, const f32x4& a1, const f32x4& b1) const {
;         const f32x4 t = (d.p[0] + d.p[1]) + (d.p[2] + d.p[3]);
;         const float inv = __builtin_amdgcn_rsqf(((t[0] + t[1]) + (t[2] + t[3])) * (1.f / DM) + EPS);
;         const f32x4 v0 = a0 * inv, v1 = b0 * inv, v2 = a1 * inv, v3 = b1 * inv;
;         if (pn < 18) { *(u32x4*)(proj + (size_t)row * PW + c0) = pack8(v0, v1); *(u32x4*)(proj + (size_t)row * PW + c0 + 128) = pack8(v2, v3); }
.LBB0_424:
	s_and_b64 vcc, exec, s[42:43]
	v_mov_b32_e32 v0, v179
	v_add_u32_e32 v22, 0xb0, v152
	v_pk_mul_f32 v[20:21], v[20:21], v[0:1] op_sel_hi:[1,0]
	v_pk_mul_f32 v[18:19], v[18:19], v[0:1] op_sel_hi:[1,0]
	v_pk_mul_f32 v[24:25], v[12:13], v[0:1] op_sel_hi:[1,0]
	v_pk_mul_f32 v[26:27], v[10:11], v[0:1] op_sel_hi:[1,0]
	s_cbranch_vccnz .LBB0_428
	s_mov_b64 s[22:23], 0
	s_mov_b64 s[0:1], 0
	s_and_saveexec_b64 s[42:43], s[40:41]
	s_cbranch_execz .LBB0_427
	v_ashrrev_i32_e32 v23, 31, v22
	v_readlane_b32 s36, v255, 22
	v_lshlrev_b64 v[28:29], 6, v[22:23]
	v_readlane_b32 s37, v255, 23
	s_mov_b64 s[0:1], exec
	v_cvt_pk_bf16_f32 v10, v18, v19
	v_cvt_pk_bf16_f32 v11, v20, v21
	v_cvt_pk_bf16_f32 v12, v26, v27
	v_cvt_pk_bf16_f32 v13, v24, v25
	s_nop 0
	v_lshl_add_u64 v[28:29], s[36:37], 0, v[28:29]
